# MFMA/VALU interleave in the MLA loop: 19 row-sum adds of the second half moved from the VALU-only tail into the empty gaps between QK^T MFMA pairs
# baseline (speedup 1.0000x reference)
; __device__ __forceinline__ void partialSM(f32x16& p0, f32x16& p1, float& m_reg, float& mn, float& alpha, const float C, const float thr) {
;     ...
;     else { mn = fmaxf(m_reg, pmax); alpha = __builtin_amdgcn_exp2f((m_reg - mn) * C); m_reg = mn; }
;     const float mnC = -mn * C;
; #pragma unroll
;     for (int r = 0; r < 16; ++r) p0[r] = fmaf(p0[r], C, mnC);
; #pragma unroll
;     for (int r = 0; r < 16; ++r) p1[r] = fmaf(p1[r], C, mnC);
; #pragma unroll
;     for (int r = 0; r < 16; ++r) p0[r] = __builtin_amdgcn_exp2f(p0[r]);
; }
; __device__ __forceinline__ void finishSM(f32x16& p0, f32x16& p1, float alpha, float& l_reg, bf16x8& pa0, bf16x8& pa1, bf16x8& pa2, bf16x8& pa3) {
; #pragma unroll
;     for (int r = 0; r < 16; ++r) p1[r] = __builtin_amdgcn_exp2f(p1[r]);
;     float ps = 0;
; #pragma unroll
;     for (int r = 0; r < 16; ++r) ps += p0[r];
; #pragma unroll
;     for (int r = 0; r < 16; ++r) ps += p1[r];
.LBB0_223:
	v_cndmask_b32_e64 v204, v130, v204, s[14:15]
	v_mul_f32_e32 v138, 0xbdd53b94, v204
	v_fmamk_f32 v80, v80, 0x3dd53b94, v138
	v_fmamk_f32 v140, v70, 0x3dd53b94, v138
	v_fmamk_f32 v70, v87, 0x3dd53b94, v138
	v_exp_f32_e32 v130, v80
	v_exp_f32_e32 v224, v70
	v_fmamk_f32 v82, v82, 0x3dd53b94, v138
	v_fmamk_f32 v84, v84, 0x3dd53b94, v138
	v_fmamk_f32 v86, v86, 0x3dd53b94, v138
	v_fmamk_f32 v88, v88, 0x3dd53b94, v138
	v_fmamk_f32 v90, v90, 0x3dd53b94, v138
	v_fmamk_f32 v92, v92, 0x3dd53b94, v138
	v_fmamk_f32 v94, v94, 0x3dd53b94, v138
	v_fmamk_f32 v145, v64, 0x3dd53b94, v138
	v_fmamk_f32 v144, v66, 0x3dd53b94, v138
	v_fmamk_f32 v143, v68, 0x3dd53b94, v138
	v_fmamk_f32 v139, v72, 0x3dd53b94, v138
	v_fmamk_f32 v146, v74, 0x3dd53b94, v138
	v_fmamk_f32 v142, v76, 0x3dd53b94, v138
	v_fmamk_f32 v141, v78, 0x3dd53b94, v138
	v_fmamk_f32 v64, v81, 0x3dd53b94, v138
	v_fmamk_f32 v66, v83, 0x3dd53b94, v138
	v_fmamk_f32 v68, v85, 0x3dd53b94, v138
	v_fmamk_f32 v72, v89, 0x3dd53b94, v138
	v_fmamk_f32 v74, v91, 0x3dd53b94, v138
	v_fmamk_f32 v76, v93, 0x3dd53b94, v138
	v_fmamk_f32 v78, v95, 0x3dd53b94, v138
	v_exp_f32_e32 v131, v82
	v_exp_f32_e32 v132, v84
	v_exp_f32_e32 v133, v86
	v_exp_f32_e32 v137, v88
	v_exp_f32_e32 v136, v90
	v_exp_f32_e32 v135, v92
	v_exp_f32_e32 v134, v94
	v_fmamk_f32 v147, v65, 0x3dd53b94, v138
	v_fmamk_f32 v156, v67, 0x3dd53b94, v138
	v_fmamk_f32 v157, v69, 0x3dd53b94, v138
	v_fmamk_f32 v191, v71, 0x3dd53b94, v138
	v_fmamk_f32 v205, v73, 0x3dd53b94, v138
	v_fmamk_f32 v207, v75, 0x3dd53b94, v138
	v_fmamk_f32 v210, v77, 0x3dd53b94, v138
	v_fmac_f32_e32 v138, 0x3dd53b94, v79
	v_exp_f32_e32 v211, v64
	v_exp_f32_e32 v212, v66
	v_exp_f32_e32 v213, v68
	v_exp_f32_e32 v228, v72
	v_exp_f32_e32 v229, v74
	v_exp_f32_e32 v230, v76
	v_exp_f32_e32 v231, v78
	s_waitcnt lgkmcnt(0)
	s_barrier
	ds_read_b128 v[64:67], v184 offset:32768
	ds_read_b128 v[68:71], v184 offset:45056
	ds_read_b128 v[148:151], v192 offset:32768
	ds_read_b128 v[152:155], v192 offset:45056
	v_exp_f32_e32 v145, v145
	v_exp_f32_e32 v147, v147
	s_waitcnt lgkmcnt(3)
	v_mfma_f32_32x32x16_bf16 v[80:95], v[64:67], v[126:129], 0
	v_exp_f32_e32 v144, v144
	v_exp_f32_e32 v143, v143
	v_exp_f32_e32 v140, v140
	v_exp_f32_e32 v139, v139
	v_exp_f32_e32 v146, v146
	v_exp_f32_e32 v142, v142
	v_exp_f32_e32 v141, v141
	s_waitcnt lgkmcnt(2)
	v_mfma_f32_32x32x16_bf16 v[64:79], v[68:71], v[126:129], 0
	v_exp_f32_e32 v138, v138
	s_waitcnt lgkmcnt(0)
	v_mfma_f32_32x32x16_bf16 v[64:79], v[152:155], v[122:125], v[64:79]
	v_mfma_f32_32x32x16_bf16 v[80:95], v[148:151], v[122:125], v[80:95]
	ds_read_b128 v[148:151], v190 offset:32768
	ds_read_b128 v[152:155], v190 offset:45056
	v_add_f32_e32 v248, 0, v130
	v_add_f32_e32 v248, v211, v248
	s_waitcnt lgkmcnt(0)
	v_mfma_f32_32x32x16_bf16 v[64:79], v[152:155], v[118:121], v[64:79]
	v_mfma_f32_32x32x16_bf16 v[80:95], v[148:151], v[118:121], v[80:95]
	ds_read_b128 v[148:151], v173 offset:32768
	ds_read_b128 v[152:155], v173 offset:45056
	v_add_f32_e32 v248, v131, v248
	v_add_f32_e32 v248, v212, v248
	s_waitcnt lgkmcnt(0)
	v_mfma_f32_32x32x16_bf16 v[64:79], v[152:155], v[114:117], v[64:79]
	v_mfma_f32_32x32x16_bf16 v[80:95], v[148:151], v[114:117], v[80:95]
	ds_read_b128 v[148:151], v184 offset:32896
	ds_read_b128 v[152:155], v184 offset:45184
	v_add_f32_e32 v248, v132, v248
	v_add_f32_e32 v248, v213, v248
	s_waitcnt lgkmcnt(0)
	v_mfma_f32_32x32x16_bf16 v[64:79], v[152:155], v[110:113], v[64:79]
	v_mfma_f32_32x32x16_bf16 v[80:95], v[148:151], v[110:113], v[80:95]
	ds_read_b128 v[148:151], v192 offset:32896
	ds_read_b128 v[152:155], v192 offset:45184
	v_add_f32_e32 v248, v133, v248
	v_add_f32_e32 v248, v224, v248
	s_waitcnt lgkmcnt(0)
	v_mfma_f32_32x32x16_bf16 v[64:79], v[152:155], v[106:109], v[64:79]
	v_mfma_f32_32x32x16_bf16 v[80:95], v[148:151], v[106:109], v[80:95]
	ds_read_b128 v[148:151], v190 offset:32896
	ds_read_b128 v[152:155], v190 offset:45184
	v_add_f32_e32 v248, v137, v248
	v_add_f32_e32 v248, v228, v248
	s_waitcnt lgkmcnt(0)
	v_mfma_f32_32x32x16_bf16 v[64:79], v[152:155], v[102:105], v[64:79]
	v_mfma_f32_32x32x16_bf16 v[80:95], v[148:151], v[102:105], v[80:95]
	ds_read_b128 v[148:151], v173 offset:32896
	ds_read_b128 v[152:155], v173 offset:45184
	v_add_f32_e32 v248, v136, v248
	v_add_f32_e32 v248, v229, v248
	s_waitcnt lgkmcnt(0)
	v_mfma_f32_32x32x16_bf16 v[64:79], v[152:155], v[98:101], v[64:79]
	v_mfma_f32_32x32x16_bf16 v[80:95], v[148:151], v[98:101], v[80:95]
	ds_read_b128 v[148:151], v184 offset:33024
	ds_read_b128 v[152:155], v184 offset:45312
	ds_read_b128 v[218:221], v181
	v_add_f32_e32 v248, v135, v248
	v_add_f32_e32 v248, v230, v248
	s_waitcnt lgkmcnt(0)
	v_mfma_f32_32x32x16_bf16 v[64:79], v[152:155], v[218:221], v[64:79]
	v_mfma_f32_32x32x16_bf16 v[80:95], v[148:151], v[218:221], v[80:95]
	ds_read_b128 v[148:151], v192 offset:33024
	ds_read_b128 v[152:155], v192 offset:45312
	ds_read_b128 v[218:221], v181 offset:8192
	v_add_f32_e32 v248, v134, v248
	v_add_f32_e32 v248, v231, v248
	s_waitcnt lgkmcnt(0)
	v_mfma_f32_32x32x16_bf16 v[64:79], v[152:155], v[218:221], v[64:79]
	v_mfma_f32_32x32x16_bf16 v[80:95], v[148:151], v[218:221], v[80:95]
	ds_read_b128 v[148:151], v190 offset:33024
	ds_read_b128 v[152:155], v190 offset:45312
	ds_read_b128 v[218:221], v181 offset:16384
	v_add_f32_e32 v248, v145, v248
	v_add_f32_e32 v248, v147, v248
	s_waitcnt lgkmcnt(0)
	v_mfma_f32_32x32x16_bf16 v[64:79], v[152:155], v[218:221], v[64:79]
	v_mfma_f32_32x32x16_bf16 v[80:95], v[148:151], v[218:221], v[80:95]
	ds_read_b128 v[148:151], v173 offset:33024
	ds_read_b128 v[152:155], v173 offset:45312
	ds_read_b128 v[218:221], v181 offset:24576
	v_add_f32_e32 v248, v144, v248
	s_waitcnt lgkmcnt(0)
; #define SBAR() __builtin_amdgcn_sched_barrier(0)
; template <int OFF> __device__ __forceinline__ s16x4 tr_read(int vb) { s16x4 r; asm volatile("ds_read_b64_tr_b16 %0, %1 offset:%2" : "=&v"(r) : "v"(vb), "i"(OFF) : "memory"); return r; }
; template <int D0> __device__ __forceinline__ void pv_one(f32x16& od, int vb, bf16x8 pa0, bf16x8 pa1, bf16x8 pa2, bf16x8 pa3) {
;     const s16x4 l0 = tr_read<v_rd_off(D0, 0, 0)>(vb), h0 = tr_read<v_rd_off(D0, 0, 1)>(vb), l1 = tr_read<v_rd_off(D0, 1, 0)>(vb), h1 = tr_read<v_rd_off(D0, 1, 1)>(vb);
;     const s16x4 l2 = tr_read<v_rd_off(D0, 2, 0)>(vb), h2 = tr_read<v_rd_off(D0, 2, 1)>(vb), l3 = tr_read<v_rd_off(D0, 3, 0)>(vb), h3 = tr_read<v_rd_off(D0, 3, 1)>(vb);
;     asm volatile("s_waitcnt lgkmcnt(0)" ::: "memory"); SBAR();
;     ...
;     od = __builtin_amdgcn_mfma_f32_32x32x16_bf16(pa0, PK(l0, h0), od, 0, 0, 0);
;     od = __builtin_amdgcn_mfma_f32_32x32x16_bf16(pa1, PK(l1, h1), od, 0, 0, 0);
;     od = __builtin_amdgcn_mfma_f32_32x32x16_bf16(pa2, PK(l2, h2), od, 0, 0, 0);
;     od = __builtin_amdgcn_mfma_f32_32x32x16_bf16(pa3, PK(l3, h3), od, 0, 0, 0);
;     ...
; }
; __device__ __forceinline__ void pv_d0(f32x16* o, int vb, bf16x8 pa0, bf16x8 pa1, bf16x8 pa2, bf16x8 pa3) {
;     pv_one<0>(o[0], vb, pa0, pa1, pa2, pa3); pv_one<1>(o[1], vb, pa0, pa1, pa2, pa3); pv_one<2>(o[2], vb, pa0, pa1, pa2, pa3); pv_one<3>(o[3], vb, pa0, pa1, pa2, pa3);
; __device__ __forceinline__ void finishSM(f32x16& p0, f32x16& p1, float alpha, float& l_reg, bf16x8& pa0, bf16x8& pa1, bf16x8& pa2, bf16x8& pa3) {
; #pragma unroll
;     for (int r = 0; r < 16; ++r) p1[r] = __builtin_amdgcn_exp2f(p1[r]);
;     float ps = 0;
; #pragma unroll
;     for (int r = 0; r < 16; ++r) ps += p0[r];
; #pragma unroll
;     for (int r = 0; r < 16; ++r) ps += p1[r];
;     { auto rr = __builtin_amdgcn_permlane32_swap(__float_as_uint(ps), __float_as_uint(ps), false, false);
;       ps = __uint_as_float(rr[0]) + __uint_as_float(rr[1]); }
;     l_reg = l_reg * alpha + ps;
;     ...
;     PK4(p0, 0, pa0); PK4(p0, 8, pa1); PK4(p1, 0, pa2); PK4(p1, 8, pa3);
;     ...
; }
	v_mfma_f32_32x32x16_bf16 v[64:79], v[152:155], v[218:221], v[64:79]
	v_mfma_f32_32x32x16_bf16 v[80:95], v[148:151], v[218:221], v[80:95]
	v_exp_f32_e32 v148, v156
	v_exp_f32_e32 v149, v157
	v_exp_f32_e32 v150, v191
	v_add_f32_e32 v154, v148, v248
	v_add_f32_e32 v154, v143, v154
	v_exp_f32_e32 v151, v205
	v_add_f32_e32 v154, v149, v154
	v_add_f32_e32 v154, v140, v154
	v_exp_f32_e32 v152, v207
	v_add_f32_e32 v154, v150, v154
	v_add_f32_e32 v154, v139, v154
	v_exp_f32_e32 v153, v210
	v_add_f32_e32 v154, v151, v154
	v_add_f32_e32 v154, v146, v154
	v_add_f32_e32 v154, v152, v154
	v_add_f32_e32 v154, v142, v154
	v_add_f32_e32 v154, v153, v154
	v_add_f32_e32 v154, v141, v154
	v_add_f32_e32 v226, v138, v154
	v_mov_b32_e32 v227, v226
	v_cvt_pk_bf16_f32 v130, v130, v211
	v_cvt_pk_bf16_f32 v131, v131, v212
	v_cvt_pk_bf16_f32 v132, v132, v213
	s_nop 1
	v_permlane32_swap_b32_e32 v226, v227
	v_cvt_pk_bf16_f32 v133, v133, v224
	v_permlane32_swap_b32_e32 v130, v132
	v_cvt_pk_bf16_f32 v154, v137, v228
	v_cvt_pk_bf16_f32 v155, v136, v229
	v_cvt_pk_bf16_f32 v156, v135, v230
	v_cvt_pk_bf16_f32 v157, v134, v231
	v_cvt_pk_bf16_f32 v218, v145, v147
	v_cvt_pk_bf16_f32 v219, v144, v148
	v_cvt_pk_bf16_f32 v220, v143, v149
	v_cvt_pk_bf16_f32 v221, v140, v150
	v_cvt_pk_bf16_f32 v228, v139, v151
	v_cvt_pk_bf16_f32 v229, v146, v152
	v_cvt_pk_bf16_f32 v230, v142, v153
	v_cvt_pk_bf16_f32 v231, v141, v138
	v_permlane32_swap_b32_e32 v131, v133
	v_permlane32_swap_b32_e32 v154, v156
	v_permlane32_swap_b32_e32 v155, v157
	v_permlane32_swap_b32_e32 v218, v220
	v_permlane32_swap_b32_e32 v219, v221
	v_permlane32_swap_b32_e32 v228, v230
	v_permlane32_swap_b32_e32 v229, v231
	s_add_i32 s38, s69, 1
	s_cmp_lt_u32 s38, s68
	s_cselect_b32 s14, 0, s68
	s_cselect_b32 s15, s25, s28
	s_lshl_b32 s14, s14, 6
	s_sub_i32 s14, s15, s14
	s_add_i32 s14, s37, s14
	s_add_i32 s14, s14, 64
	s_ashr_i32 s15, s14, 31
	v_lshl_add_u64 v[134:135], s[14:15], 0, v[174:175]
	v_lshl_add_u64 v[136:137], v[176:177], 0, s[14:15]
	v_lshlrev_b64 v[134:135], 12, v[134:135]
	v_lshlrev_b64 v[136:137], 12, v[136:137]
	v_lshl_add_u64 v[134:135], v[178:179], 0, v[134:135]
	v_lshl_add_u64 v[138:139], v[178:179], 0, v[136:137]
	v_mad_i64_i32 v[142:143], s[20:21], v164, s14, 0
	v_mad_i64_i32 v[146:147], s[20:21], v168, s14, 0
	v_mad_i64_i32 v[150:151], s[14:15], v172, s14, 0
	global_load_dwordx4 v[134:137], v[134:135], off offset:256
	s_nop 0
	global_load_dwordx4 v[138:141], v[138:139], off offset:256
	v_lshl_add_u64 v[142:143], v[142:143], 1, v[162:163]
	v_lshl_add_u64 v[146:147], v[146:147], 1, v[166:167]
	v_lshl_add_u64 v[150:151], v[150:151], 1, v[170:171]
	global_load_dwordx4 v[142:145], v[142:143], off
	s_nop 0
	global_load_dwordx4 v[146:149], v[146:147], off
	s_nop 0
	global_load_dwordx4 v[150:153], v[150:151], off
	ds_read_b64_tr_b16 v[232:233], v169 offset:0
	ds_read_b64_tr_b16 v[234:235], v169 offset:0x800
	ds_read_b64_tr_b16 v[236:237], v169 offset:0x1000
	ds_read_b64_tr_b16 v[238:239], v169 offset:0x1800
	ds_read_b64_tr_b16 v[240:241], v169 offset:0x2000
	ds_read_b64_tr_b16 v[242:243], v169 offset:0x2800
	ds_read_b64_tr_b16 v[244:245], v169 offset:0x3000
	ds_read_b64_tr_b16 v[246:247], v169 offset:0x3800
	s_waitcnt lgkmcnt(0)
	s_nop 0
	v_mfma_f32_32x32x16_bf16 v[48:63], v[130:133], v[232:235], v[48:63]
	ds_read_b64_tr_b16 v[232:233], v169 offset:0x200
	ds_read_b64_tr_b16 v[234:235], v169 offset:0xa00
	v_mfma_f32_32x32x16_bf16 v[48:63], v[154:157], v[236:239], v[48:63]
	ds_read_b64_tr_b16 v[236:237], v169 offset:0x1200
	ds_read_b64_tr_b16 v[238:239], v169 offset:0x1a00
	v_mfma_f32_32x32x16_bf16 v[48:63], v[218:221], v[240:243], v[48:63]
	ds_read_b64_tr_b16 v[240:241], v169 offset:0x2200
	ds_read_b64_tr_b16 v[242:243], v169 offset:0x2a00
	v_mfma_f32_32x32x16_bf16 v[48:63], v[228:231], v[244:247], v[48:63]
	ds_read_b64_tr_b16 v[244:245], v169 offset:0x3200
	ds_read_b64_tr_b16 v[246:247], v169 offset:0x3a00
	s_waitcnt lgkmcnt(6)
	v_mfma_f32_32x32x16_bf16 v[32:47], v[130:133], v[232:235], v[32:47]
	ds_read_b64_tr_b16 v[232:233], v169 offset:0x400
	ds_read_b64_tr_b16 v[234:235], v169 offset:0xc00
	s_waitcnt lgkmcnt(6)
	v_mfma_f32_32x32x16_bf16 v[32:47], v[154:157], v[236:239], v[32:47]
	ds_read_b64_tr_b16 v[236:237], v169 offset:0x1400
	ds_read_b64_tr_b16 v[238:239], v169 offset:0x1c00
	s_waitcnt lgkmcnt(6)
	v_mfma_f32_32x32x16_bf16 v[32:47], v[218:221], v[240:243], v[32:47]
	ds_read_b64_tr_b16 v[240:241], v169 offset:0x2400
	ds_read_b64_tr_b16 v[242:243], v169 offset:0x2c00
	s_waitcnt lgkmcnt(6)
	v_mfma_f32_32x32x16_bf16 v[32:47], v[228:231], v[244:247], v[32:47]
	ds_read_b64_tr_b16 v[244:245], v169 offset:0x3400
	ds_read_b64_tr_b16 v[246:247], v169 offset:0x3c00
	s_waitcnt lgkmcnt(6)
	v_mfma_f32_32x32x16_bf16 v[16:31], v[130:133], v[232:235], v[16:31]
	ds_read_b64_tr_b16 v[232:233], v169 offset:0x600
	ds_read_b64_tr_b16 v[234:235], v169 offset:0xe00
	s_waitcnt lgkmcnt(6)
	v_mfma_f32_32x32x16_bf16 v[16:31], v[154:157], v[236:239], v[16:31]
	ds_read_b64_tr_b16 v[236:237], v169 offset:0x1600
	ds_read_b64_tr_b16 v[238:239], v169 offset:0x1e00
	s_waitcnt lgkmcnt(6)
	v_mfma_f32_32x32x16_bf16 v[16:31], v[218:221], v[240:243], v[16:31]
	ds_read_b64_tr_b16 v[240:241], v169 offset:0x2600
	ds_read_b64_tr_b16 v[242:243], v169 offset:0x2e00
	s_waitcnt lgkmcnt(6)
	v_mfma_f32_32x32x16_bf16 v[16:31], v[228:231], v[244:247], v[16:31]
	ds_read_b64_tr_b16 v[244:245], v169 offset:0x3600
	ds_read_b64_tr_b16 v[246:247], v169 offset:0x3e00
	s_waitcnt lgkmcnt(6)
	v_mfma_f32_32x32x16_bf16 v[0:15], v[130:133], v[232:235], v[0:15]
	v_max_f32_e32 v130, v81, v81
	v_max_f32_e32 v131, v80, v80
	v_max_f32_e32 v130, v131, v130
	v_max3_f32 v130, v130, v82, v83
	v_max3_f32 v130, v130, v84, v85
	v_max3_f32 v130, v130, v86, v87
	v_max3_f32 v130, v130, v88, v89
	v_max3_f32 v130, v130, v90, v91
	v_max3_f32 v130, v130, v92, v93
	s_waitcnt lgkmcnt(4)
	v_mfma_f32_32x32x16_bf16 v[0:15], v[154:157], v[236:239], v[0:15]
	v_max3_f32 v130, v130, v94, v95
	v_max3_f32 v130, v130, v64, v65
	v_max3_f32 v130, v130, v66, v67
	v_max3_f32 v130, v130, v68, v69
	v_max3_f32 v130, v130, v70, v71
	v_max3_f32 v130, v130, v72, v73
	v_max3_f32 v130, v130, v74, v75
	v_max3_f32 v130, v130, v76, v77
	s_waitcnt lgkmcnt(2)
	v_mfma_f32_32x32x16_bf16 v[0:15], v[218:221], v[240:243], v[0:15]
	v_max3_f32 v130, v130, v78, v79
	v_mov_b32_e32 v131, v130
	s_nop 1
	v_permlane32_swap_b32_e32 v130, v131
	v_max_f32_e32 v131, v131, v131
	v_max_f32_e32 v130, v130, v130
	v_max_f32_e32 v130, v130, v131
	v_sub_f32_e32 v131, v130, v204
	v_cmp_ge_f32_e32 vcc, s72, v131
	v_max_f32_e32 v131, v204, v204
	v_max_f32_e32 v130, v131, v130
	s_waitcnt lgkmcnt(0)
	v_mfma_f32_32x32x16_bf16 v[0:15], v[228:231], v[244:247], v[0:15]
	v_sub_f32_e32 v131, v204, v130
	v_mul_f32_e32 v131, 0x3dd53b94, v131
	v_exp_f32_e32 v131, v131
	s_cmp_eq_u64 vcc, exec
	s_cselect_b64 s[14:15], -1, 0
	v_cndmask_b32_e64 v224, v131, 1.0, s[14:15]
	v_cmp_gt_f32_e32 vcc, 1.0, v224
	s_barrier
; #define SWRITE(b, i) do { *(bf16x8*)(V_lds + (b) * SHM_V + vst0) = sr_[i].vs0; *(bf16x8*)(V_lds + (b) * SHM_V + vst1) = sr_[i].vs1; \
;     _Pragma("unroll") for (int c_ = 0; c_ < KCH; ++c_) *(bf16x8*)(K_lds + (b) * SHM_K + kwo[c_]) = sr_[i].ks[c_]; } while (0)
; #define RESC(al) do { if (__any((al) < 1.f)) { if (hi == 0) al_l[r32] = (al); asm volatile("s_waitcnt lgkmcnt(0)" ::: "memory"); \
;     _Pragma("unroll") for (int d = 0; d < 4; ++d) _Pragma("unroll") for (int r = 0; r < 16; ++r) o[d][r] *= al_l[crow(r, hi)]; } } while (0)
; template <int DQK, int DK1, int LDQ, int LDK, int LDKR, int LDV, int NQL, int SDEPTH>
; __device__ __forceinline__ void attn_core(const AttnArgs& a, char* lds, f32x16 (&o)[4]) {
;     ...
;         __syncthreads(); SWRITE(0, SE);
;         RESC(alB); __syncthreads();
	s_waitcnt vmcnt(4)
	ds_write_b128 v186, v[134:137] offset:16384
	s_waitcnt vmcnt(3)
	ds_write_b128 v188, v[138:141] offset:16384
	s_waitcnt vmcnt(2)
	ds_write_b128 v194, v[142:145] offset:57344
	s_waitcnt vmcnt(1)
	ds_write_b128 v196, v[146:149] offset:57344
	s_waitcnt vmcnt(0)
	ds_write_b128 v198, v[150:153] offset:57344
	s_cbranch_vccz .LBB0_227
	s_and_saveexec_b64 s[20:21], s[12:13]
	ds_write_b32 v165, v224 offset:128
	s_or_b64 exec, exec, s[20:21]
	s_waitcnt lgkmcnt(0)
	v_add_u32_e32 v131, v161, v96
	ds_read_b128 v[132:135], v131 offset:224
	ds_read_b128 v[136:139], v131 offset:192
	ds_read_b128 v[140:143], v131 offset:160
	ds_read_b128 v[144:147], v131 offset:128
	s_waitcnt lgkmcnt(3)
	v_pk_mul_f32 v[60:61], v[60:61], v[132:133]
	s_waitcnt lgkmcnt(2)
	v_pk_mul_f32 v[56:57], v[56:57], v[136:137]
	s_waitcnt lgkmcnt(1)
	v_pk_mul_f32 v[52:53], v[52:53], v[140:141]
	v_pk_mul_f32 v[62:63], v[62:63], v[134:135]
	v_pk_mul_f32 v[58:59], v[58:59], v[138:139]
	v_pk_mul_f32 v[54:55], v[54:55], v[142:143]
	s_waitcnt lgkmcnt(0)
	v_pk_mul_f32 v[50:51], v[50:51], v[146:147]
	v_pk_mul_f32 v[48:49], v[48:49], v[144:145]
	v_pk_mul_f32 v[44:45], v[44:45], v[132:133]
	v_pk_mul_f32 v[40:41], v[40:41], v[136:137]
	v_pk_mul_f32 v[36:37], v[36:37], v[140:141]
	v_pk_mul_f32 v[46:47], v[46:47], v[134:135]
	v_pk_mul_f32 v[42:43], v[42:43], v[138:139]
	v_pk_mul_f32 v[38:39], v[38:39], v[142:143]
	v_pk_mul_f32 v[34:35], v[34:35], v[146:147]
	v_pk_mul_f32 v[32:33], v[32:33], v[144:145]
	v_pk_mul_f32 v[28:29], v[28:29], v[132:133]
	v_pk_mul_f32 v[24:25], v[24:25], v[136:137]
	v_pk_mul_f32 v[20:21], v[20:21], v[140:141]
	v_pk_mul_f32 v[30:31], v[30:31], v[134:135]
	v_pk_mul_f32 v[26:27], v[26:27], v[138:139]
	v_pk_mul_f32 v[22:23], v[22:23], v[142:143]
	v_pk_mul_f32 v[18:19], v[18:19], v[146:147]
	v_pk_mul_f32 v[16:17], v[16:17], v[144:145]
	v_pk_mul_f32 v[12:13], v[12:13], v[132:133]
	v_pk_mul_f32 v[8:9], v[8:9], v[136:137]
	v_pk_mul_f32 v[4:5], v[4:5], v[140:141]
	v_pk_mul_f32 v[14:15], v[14:15], v[134:135]
	v_pk_mul_f32 v[10:11], v[10:11], v[138:139]
	v_pk_mul_f32 v[6:7], v[6:7], v[142:143]
	v_pk_mul_f32 v[2:3], v[2:3], v[146:147]
	v_pk_mul_f32 v[0:1], v[0:1], v[144:145]
